# fp8 GEMM tiles: plain v_mfma_f32_16x16x128_f8f6f4 (e4m3 x e4m3) instead of the block-scaled form whose scales were all 2^0; same numerics, half the instruction bytes
# speedup vs baseline: 1.0060x; 1.0060x over previous
.LBB0_212:
	s_add_u32 s9, s10, 0xfffe0080
	s_addc_u32 s56, s11, -1
	s_add_i32 s8, 0, 0x10000
	s_cmp_eq_u32 s94, 4
	s_cselect_b32 s75, s31, s56
	s_cselect_b32 s74, s90, s9
	s_cselect_b32 s73, s35, s93
	s_cselect_b32 s72, s91, s92
	s_add_i32 s9, 0, 0x14000
	v_add_u32_e32 v0, s8, v208
	v_add_u32_e32 v12, s9, v208
	ds_read_b128 v[16:19], v0
	ds_read_b128 v[20:23], v0 offset:1024
	ds_read_b128 v[24:27], v0 offset:2048
	ds_read_b128 v[28:31], v0 offset:3072
	ds_read_b128 v[0:3], v12
	ds_read_b128 v[4:7], v12 offset:1024
	ds_read_b128 v[8:11], v12 offset:2048
	ds_read_b128 v[12:15], v12 offset:3072
	v_lshl_add_u64 v[194:195], s[10:11], 0, v[168:169]
	s_add_i32 m0, s83, 0xc000
	ds_read_b128 v[172:175], v210
	ds_read_b128 v[176:179], v210 offset:1024
	ds_read_b128 v[228:231], v210 offset:2048
	ds_read_b128 v[232:235], v210 offset:3072
	ds_read_b128 v[236:239], v210 offset:4096
	ds_read_b128 v[240:243], v210 offset:5120
	ds_read_b128 v[186:189], v210 offset:6144
	ds_read_b128 v[190:193], v210 offset:7168
	global_load_lds_dwordx4 v[194:195], off
	v_lshl_add_u64 v[194:195], s[10:11], 0, v[170:171]
	s_add_i32 m0, s83, 0xe000
	s_nop 0
	global_load_lds_dwordx4 v[194:195], off
	s_waitcnt vmcnt(8)
	s_waitcnt lgkmcnt(0)
	s_barrier
	s_setprio 1
	s_waitcnt lgkmcnt(0)
	v_mfma_f32_16x16x128_f8f6f4 v[158:161], v[16:23], v[172:179], v[158:161]
	v_mfma_f32_16x16x128_f8f6f4 v[154:157], v[24:31], v[172:179], v[154:157]
	v_mfma_f32_16x16x128_f8f6f4 v[142:145], v[16:23], v[228:235], v[142:145]
	v_mfma_f32_16x16x128_f8f6f4 v[138:141], v[24:31], v[228:235], v[138:141]
	v_mfma_f32_16x16x128_f8f6f4 v[126:129], v[16:23], v[236:243], v[126:129]
	v_mfma_f32_16x16x128_f8f6f4 v[122:125], v[24:31], v[236:243], v[122:125]
	v_mfma_f32_16x16x128_f8f6f4 v[110:113], v[16:23], v[186:193], v[110:113]
	v_mfma_f32_16x16x128_f8f6f4 v[106:109], v[24:31], v[186:193], v[106:109]
	s_setprio 0
	s_setprio 1
	v_mfma_f32_16x16x128_f8f6f4 v[150:153], v[0:7], v[172:179], v[150:153]
	v_mfma_f32_16x16x128_f8f6f4 v[146:149], v[8:15], v[172:179], v[146:149]
	v_mfma_f32_16x16x128_f8f6f4 v[134:137], v[0:7], v[228:235], v[134:137]
	v_mfma_f32_16x16x128_f8f6f4 v[130:133], v[8:15], v[228:235], v[130:133]
	v_mfma_f32_16x16x128_f8f6f4 v[118:121], v[0:7], v[236:243], v[118:121]
	v_mfma_f32_16x16x128_f8f6f4 v[114:117], v[8:15], v[236:243], v[114:117]
	v_mfma_f32_16x16x128_f8f6f4 v[102:105], v[0:7], v[186:193], v[102:105]
	v_mfma_f32_16x16x128_f8f6f4 v[98:101], v[8:15], v[186:193], v[98:101]
	s_setprio 0
	s_barrier
	s_add_i32 s8, s8, s77
	v_lshl_add_u64 v[172:173], s[72:73], 0, v[32:33]
	s_mov_b32 m0, s8
	ds_read_b128 v[186:189], v210 offset:16384
	ds_read_b128 v[190:193], v210 offset:17408
	ds_read_b128 v[228:231], v210 offset:18432
	ds_read_b128 v[232:235], v210 offset:19456
	ds_read_b128 v[236:239], v210 offset:20480
	ds_read_b128 v[240:243], v210 offset:21504
	ds_read_b128 v[194:197], v210 offset:22528
	ds_read_b128 v[198:201], v210 offset:23552
	global_load_lds_dwordx4 v[172:173], off
	s_add_i32 m0, s8, 0x2000
	s_add_u32 s96, s72, 0x20000
	v_lshl_add_u64 v[174:175], s[72:73], 0, v[166:167]
	s_addc_u32 s97, s73, 0
	s_add_i32 s8, s9, s77
	global_load_lds_dwordx4 v[174:175], off
	v_lshl_add_u64 v[176:177], s[96:97], 0, v[32:33]
	s_mov_b32 m0, s8
	v_lshl_add_u64 v[178:179], s[74:75], 0, v[164:165]
	global_load_lds_dwordx4 v[176:177], off
	v_lshl_add_u64 v[176:177], s[96:97], 0, v[166:167]
	s_add_i32 m0, s8, 0x2000
	s_nop 0
	global_load_lds_dwordx4 v[176:177], off
	v_lshl_add_u64 v[176:177], s[74:75], 0, v[162:163]
	s_mov_b32 m0, s83
	s_nop 0
	global_load_lds_dwordx4 v[176:177], off
	s_mov_b32 m0, s16
	s_nop 0
	global_load_lds_dwordx4 v[178:179], off
	s_waitcnt vmcnt(8)
	s_waitcnt lgkmcnt(0)
	s_barrier
	s_setprio 1
	s_waitcnt lgkmcnt(0)
	v_mfma_f32_16x16x128_f8f6f4 v[94:97], v[16:23], v[186:193], v[94:97]
	v_mfma_f32_16x16x128_f8f6f4 v[90:93], v[24:31], v[186:193], v[90:93]
	v_mfma_f32_16x16x128_f8f6f4 v[78:81], v[16:23], v[228:235], v[78:81]
	v_mfma_f32_16x16x128_f8f6f4 v[74:77], v[24:31], v[228:235], v[74:77]
	v_mfma_f32_16x16x128_f8f6f4 v[62:65], v[16:23], v[236:243], v[62:65]
	v_mfma_f32_16x16x128_f8f6f4 v[58:61], v[24:31], v[236:243], v[58:61]
	v_mfma_f32_16x16x128_f8f6f4 v[46:49], v[16:23], v[194:201], v[46:49]
	v_mfma_f32_16x16x128_f8f6f4 v[42:45], v[24:31], v[194:201], v[42:45]
	s_setprio 0
	s_setprio 1
	v_mfma_f32_16x16x128_f8f6f4 v[86:89], v[0:7], v[186:193], v[86:89]
	v_mfma_f32_16x16x128_f8f6f4 v[82:85], v[8:15], v[186:193], v[82:85]
	v_mfma_f32_16x16x128_f8f6f4 v[70:73], v[0:7], v[228:235], v[70:73]
	v_mfma_f32_16x16x128_f8f6f4 v[66:69], v[8:15], v[228:235], v[66:69]
	v_mfma_f32_16x16x128_f8f6f4 v[54:57], v[0:7], v[236:243], v[54:57]
	v_mfma_f32_16x16x128_f8f6f4 v[50:53], v[8:15], v[236:243], v[50:53]
	v_mfma_f32_16x16x128_f8f6f4 v[38:41], v[0:7], v[194:201], v[38:41]
	v_mfma_f32_16x16x128_f8f6f4 v[34:37], v[8:15], v[194:201], v[34:37]
	s_setprio 0
	s_barrier
	s_add_i32 s56, 0, 0x18000
	s_add_i32 s57, 0, 0x1c000
	v_add_u32_e32 v12, s56, v208
	v_add_u32_e32 v28, s57, v208
	ds_read_b128 v[0:3], v12
	ds_read_b128 v[4:7], v12 offset:1024
	ds_read_b128 v[8:11], v12 offset:2048
	ds_read_b128 v[12:15], v12 offset:3072
	ds_read_b128 v[16:19], v28
	ds_read_b128 v[20:23], v28 offset:1024
	ds_read_b128 v[24:27], v28 offset:2048
	ds_read_b128 v[28:31], v28 offset:3072
	s_add_u32 s8, s74, 0x20000
	s_addc_u32 s9, s75, 0
	s_mov_b32 m0, s17
	v_lshl_add_u64 v[244:245], s[8:9], 0, v[162:163]
	ds_read_b128 v[186:189], v210 offset:32768
	ds_read_b128 v[190:193], v210 offset:33792
	ds_read_b128 v[194:197], v210 offset:34816
	ds_read_b128 v[198:201], v210 offset:35840
	ds_read_b128 v[228:231], v210 offset:36864
	ds_read_b128 v[232:235], v210 offset:37888
	ds_read_b128 v[236:239], v210 offset:38912
	ds_read_b128 v[240:243], v210 offset:39936
	global_load_lds_dwordx4 v[244:245], off
	v_lshl_add_u64 v[244:245], s[8:9], 0, v[164:165]
	s_mov_b32 m0, s84
	s_nop 0
	global_load_lds_dwordx4 v[244:245], off
	s_waitcnt vmcnt(8)
	s_waitcnt lgkmcnt(0)
	s_barrier
	s_setprio 1
	s_waitcnt lgkmcnt(0)
	v_mfma_f32_16x16x128_f8f6f4 v[158:161], v[0:7], v[186:193], v[158:161]
	v_mfma_f32_16x16x128_f8f6f4 v[154:157], v[8:15], v[186:193], v[154:157]
	v_mfma_f32_16x16x128_f8f6f4 v[142:145], v[0:7], v[194:201], v[142:145]
	v_mfma_f32_16x16x128_f8f6f4 v[138:141], v[8:15], v[194:201], v[138:141]
	v_mfma_f32_16x16x128_f8f6f4 v[126:129], v[0:7], v[228:235], v[126:129]
	v_mfma_f32_16x16x128_f8f6f4 v[122:125], v[8:15], v[228:235], v[122:125]
	v_mfma_f32_16x16x128_f8f6f4 v[110:113], v[0:7], v[236:243], v[110:113]
	v_mfma_f32_16x16x128_f8f6f4 v[106:109], v[8:15], v[236:243], v[106:109]
	s_setprio 0
	s_setprio 1
	v_mfma_f32_16x16x128_f8f6f4 v[150:153], v[16:23], v[186:193], v[150:153]
	v_mfma_f32_16x16x128_f8f6f4 v[146:149], v[24:31], v[186:193], v[146:149]
	v_mfma_f32_16x16x128_f8f6f4 v[134:137], v[16:23], v[194:201], v[134:137]
	v_mfma_f32_16x16x128_f8f6f4 v[130:133], v[24:31], v[194:201], v[130:133]
	v_mfma_f32_16x16x128_f8f6f4 v[118:121], v[16:23], v[228:235], v[118:121]
	v_mfma_f32_16x16x128_f8f6f4 v[114:117], v[24:31], v[228:235], v[114:117]
	v_mfma_f32_16x16x128_f8f6f4 v[102:105], v[16:23], v[236:243], v[102:105]
	v_mfma_f32_16x16x128_f8f6f4 v[98:101], v[24:31], v[236:243], v[98:101]
	s_setprio 0
	s_barrier
	s_add_i32 s8, s56, s77
	v_lshl_add_u64 v[172:173], v[172:173], 0, s[38:39]
	s_mov_b32 m0, s8
	ds_read_b128 v[186:189], v210 offset:49152
	ds_read_b128 v[190:193], v210 offset:50176
	ds_read_b128 v[194:197], v210 offset:51200
	ds_read_b128 v[198:201], v210 offset:52224
	ds_read_b128 v[228:231], v210 offset:53248
	ds_read_b128 v[232:235], v210 offset:54272
	ds_read_b128 v[236:239], v210 offset:55296
	ds_read_b128 v[240:243], v210 offset:56320
	global_load_lds_dwordx4 v[172:173], off
	s_add_i32 m0, s8, 0x2000
	s_add_u32 s8, s72, 0x20080
	v_lshl_add_u64 v[172:173], v[174:175], 0, s[38:39]
	s_addc_u32 s9, s73, 0
	s_add_i32 s56, s57, s77
	global_load_lds_dwordx4 v[172:173], off
	v_lshl_add_u64 v[172:173], s[8:9], 0, v[32:33]
	s_mov_b32 m0, s56
	s_nop 0
	global_load_lds_dwordx4 v[172:173], off
	v_lshl_add_u64 v[172:173], s[8:9], 0, v[166:167]
	s_add_i32 m0, s56, 0x2000
	s_nop 0
	global_load_lds_dwordx4 v[172:173], off
	v_lshl_add_u64 v[172:173], v[176:177], 0, s[38:39]
	s_mov_b32 m0, s85
	s_nop 0
	global_load_lds_dwordx4 v[172:173], off
	v_lshl_add_u64 v[172:173], v[178:179], 0, s[38:39]
	s_mov_b32 m0, s86
	s_nop 0
	global_load_lds_dwordx4 v[172:173], off
	s_waitcnt vmcnt(8)
	s_waitcnt lgkmcnt(0)
	s_barrier
	s_setprio 1
	s_waitcnt lgkmcnt(0)
	v_mfma_f32_16x16x128_f8f6f4 v[94:97], v[0:7], v[186:193], v[94:97]
	v_mfma_f32_16x16x128_f8f6f4 v[90:93], v[8:15], v[186:193], v[90:93]
	v_mfma_f32_16x16x128_f8f6f4 v[78:81], v[0:7], v[194:201], v[78:81]
	v_mfma_f32_16x16x128_f8f6f4 v[74:77], v[8:15], v[194:201], v[74:77]
	v_mfma_f32_16x16x128_f8f6f4 v[62:65], v[0:7], v[228:235], v[62:65]
	v_mfma_f32_16x16x128_f8f6f4 v[58:61], v[8:15], v[228:235], v[58:61]
	v_mfma_f32_16x16x128_f8f6f4 v[46:49], v[0:7], v[236:243], v[46:49]
	v_mfma_f32_16x16x128_f8f6f4 v[42:45], v[8:15], v[236:243], v[42:45]
	s_setprio 0
	s_setprio 1
	v_mfma_f32_16x16x128_f8f6f4 v[86:89], v[16:23], v[186:193], v[86:89]
	v_mfma_f32_16x16x128_f8f6f4 v[82:85], v[24:31], v[186:193], v[82:85]
	v_mfma_f32_16x16x128_f8f6f4 v[70:73], v[16:23], v[194:201], v[70:73]
	v_mfma_f32_16x16x128_f8f6f4 v[66:69], v[24:31], v[194:201], v[66:69]
	v_mfma_f32_16x16x128_f8f6f4 v[54:57], v[16:23], v[228:235], v[54:57]
	v_mfma_f32_16x16x128_f8f6f4 v[50:53], v[24:31], v[228:235], v[50:53]
	v_mfma_f32_16x16x128_f8f6f4 v[38:41], v[16:23], v[236:243], v[38:41]
	v_mfma_f32_16x16x128_f8f6f4 v[34:37], v[24:31], v[236:243], v[34:37]
	s_setprio 0
	s_barrier
	s_add_i32 s94, s94, 2
	s_add_u32 s10, s10, 0x100
	s_addc_u32 s11, s11, 0
	s_add_u32 s92, s92, 0x100
	s_addc_u32 s93, s93, 0
	s_cmp_gt_u32 s94, 5
	s_cbranch_scc0 .LBB0_212
	s_and_b64 vcc, exec, s[20:21]
	s_cbranch_vccz .LBB0_215
	s_barrier

.LBB0_485:
	v_readlane_b32 s16, v254, 30
	v_mov_b32_e32 v163, v33
	v_readlane_b32 s17, v254, 31
	v_mov_b32_e32 v165, v33
	s_lshl_b32 s2, s14, 5
	v_lshl_add_u64 v[90:91], s[16:17], 0, v[162:163]
	v_lshl_add_u64 v[92:93], s[16:17], 0, v[164:165]
	s_add_i32 s17, 0, 0x18000
	s_and_b32 s45, s2, 0x60
	s_add_i32 s2, s17, s9
	s_lshl_b32 s16, s44, 13
	v_lshl_add_u64 v[68:69], v[78:79], 0, s[38:39]
	s_mov_b32 m0, s2
	s_add_i32 s73, s2, 0x2000
	s_add_i32 s67, s77, 0x8000
	s_add_i32 s74, s77, 0xa000
	s_waitcnt vmcnt(2)
	s_barrier
	global_load_lds_dwordx4 v[68:69], off
	v_lshl_add_u64 v[70:71], v[80:81], 0, s[38:39]
	s_mov_b32 m0, s73
	s_add_u32 s14, s10, 0x20080
	global_load_lds_dwordx4 v[70:71], off
	v_lshl_add_u64 v[66:67], v[90:91], 0, s[38:39]
	s_mov_b32 m0, s67
	s_addc_u32 s15, s11, 0
	s_add_i32 s18, 0, 0x1c000
	global_load_lds_dwordx4 v[66:67], off
	v_lshl_add_u64 v[72:73], v[92:93], 0, s[38:39]
	s_mov_b32 m0, s74
	s_add_i32 s75, s18, s9
	global_load_lds_dwordx4 v[72:73], off
	v_lshl_add_u64 v[74:75], s[14:15], 0, v[32:33]
	s_mov_b32 m0, s75
	s_add_i32 s76, s75, 0x2000
	global_load_lds_dwordx4 v[74:75], off
	v_lshl_add_u64 v[76:77], s[14:15], 0, v[166:167]
	s_mov_b32 m0, s76
	v_lshlrev_b32_e32 v1, 2, v213
	global_load_lds_dwordx4 v[76:77], off
	v_lshl_or_b32 v0, v213, 6, v214
	v_and_b32_e32 v1, 32, v1
	v_bitop3_b32 v0, v0, s16, v1 bitop3:0xde
	v_lshl_or_b32 v1, s45, 7, v215
	s_add_i32 s85, 0, 0x10000
	v_add_u32_e32 v98, s85, v1
	s_add_i32 s85, s85, s9
	s_add_i32 s87, 0, 0x14000
	s_add_i32 s89, s77, 0xc000
	s_add_i32 s88, s77, 0xe000
	s_add_i32 s84, s85, 0x2000
	s_add_u32 s34, s10, 0x20100
	v_add_u32_e32 v97, s87, v1
	s_addc_u32 s35, s11, 0
	s_add_i32 s87, s87, s9
	s_waitcnt vmcnt(6)
	s_barrier
	s_add_i32 s86, s87, 0x2000
	ds_read_b128 v[4:7], v98
	ds_read_b128 v[8:11], v98 offset:1024
	ds_read_b128 v[16:19], v98 offset:2048
	ds_read_b128 v[20:23], v98 offset:3072
	ds_read_b128 v[100:103], v97
	ds_read_b128 v[104:107], v97 offset:1024
	ds_read_b128 v[108:111], v97 offset:2048
	ds_read_b128 v[112:115], v97 offset:3072
	s_add_u32 s20, s10, 0x20180
	s_addc_u32 s21, s11, 0
	v_add_u32_e32 v95, s18, v1
	s_add_u32 s18, s10, 0x20200
	s_addc_u32 s19, s11, 0
	v_readlane_b32 s14, v254, 16
	s_add_u32 s16, s10, 0x20280
	v_readlane_b32 s15, v254, 17
	v_add_u32_e32 v96, s17, v1
	s_addc_u32 s17, s11, 0
	v_lshl_add_u64 v[86:87], s[14:15], 0, v[162:163]
	v_lshl_add_u64 v[88:89], s[14:15], 0, v[164:165]
	s_add_u32 s14, s10, 0x20300
	s_addc_u32 s15, s11, 0
	s_add_u32 s10, s10, 0x20380
	s_addc_u32 s11, s11, 0
	v_add_u32_e32 v94, 0, v0
	s_cmpk_gt_u32 s8, 0xff
	v_readlane_b32 s8, v254, 18
	v_readlane_b32 s9, v254, 19
	s_mov_b32 m0, s89
	ds_read_b128 v[34:37], v94
	ds_read_b128 v[38:41], v94 offset:1024
	ds_read_b128 v[116:119], v94 offset:2048
	ds_read_b128 v[120:123], v94 offset:3072
	ds_read_b128 v[124:127], v94 offset:4096
	ds_read_b128 v[128:131], v94 offset:5120
	ds_read_b128 v[132:135], v94 offset:6144
	ds_read_b128 v[136:139], v94 offset:7168
	v_lshl_add_u64 v[0:1], s[8:9], 0, v[162:163]
	global_load_lds_dwordx4 v[0:1], off
	v_lshl_add_u64 v[0:1], s[8:9], 0, v[164:165]
	s_mov_b32 m0, s88
	s_nop 0
	global_load_lds_dwordx4 v[0:1], off
	s_waitcnt vmcnt(8)
	s_waitcnt lgkmcnt(0)
	s_barrier
	s_setprio 1
	s_mov_b32 s28, s29
	s_mov_b32 s30, s29
	s_mov_b32 s31, s29
	v_mov_b64_e32 v[64:65], s[30:31]
	v_mov_b64_e32 v[60:61], s[30:31]
	v_mov_b64_e32 v[48:49], s[30:31]
	v_mov_b64_e32 v[44:45], s[30:31]
	v_mov_b64_e32 v[28:29], s[28:29]
	v_mov_b64_e32 v[24:25], s[28:29]
	v_mov_b64_e32 v[12:13], s[28:29]
	v_mov_b64_e32 v[62:63], s[28:29]
	v_mov_b64_e32 v[58:59], s[28:29]
	v_mov_b64_e32 v[46:47], s[28:29]
	v_mov_b64_e32 v[42:43], s[28:29]
	v_mov_b64_e32 v[30:31], s[30:31]
	v_mov_b64_e32 v[26:27], s[30:31]
	v_mov_b64_e32 v[14:15], s[30:31]
	v_mov_b64_e32 v[0:1], s[28:29]
	s_waitcnt lgkmcnt(0)
	v_mfma_f32_16x16x128_f8f6f4 v[62:65], v[4:11], v[34:41], v[62:65]
	v_mfma_f32_16x16x128_f8f6f4 v[58:61], v[16:23], v[34:41], v[58:61]
	v_mfma_f32_16x16x128_f8f6f4 v[46:49], v[4:11], v[116:123], v[46:49]
	v_mfma_f32_16x16x128_f8f6f4 v[42:45], v[16:23], v[116:123], v[42:45]
	v_mfma_f32_16x16x128_f8f6f4 v[28:31], v[4:11], v[124:131], v[28:31]
	v_mfma_f32_16x16x128_f8f6f4 v[24:27], v[16:23], v[124:131], v[24:27]
	v_mfma_f32_16x16x128_f8f6f4 v[12:15], v[4:11], v[132:139], v[12:15]
	v_mov_b64_e32 v[8:9], s[28:29]
	v_mov_b64_e32 v[2:3], s[30:31]
	v_mov_b64_e32 v[10:11], s[30:31]
	v_mfma_f32_16x16x128_f8f6f4 v[8:11], v[16:23], v[132:139], v[8:11]
	s_setprio 0
	s_setprio 1
	v_mov_b64_e32 v[56:57], s[30:31]
	v_mov_b64_e32 v[52:53], s[30:31]
	v_mov_b64_e32 v[54:55], s[28:29]
	v_mov_b64_e32 v[50:51], s[28:29]
	v_mfma_f32_16x16x128_f8f6f4 v[54:57], v[100:107], v[34:41], v[54:57]
	v_mfma_f32_16x16x128_f8f6f4 v[50:53], v[108:115], v[34:41], v[50:53]
	v_mov_b64_e32 v[40:41], s[30:31]
	v_mov_b64_e32 v[36:37], s[30:31]
	v_mov_b64_e32 v[20:21], s[28:29]
	v_mov_b64_e32 v[16:17], s[28:29]
	v_mov_b64_e32 v[4:5], s[28:29]
	v_mov_b64_e32 v[38:39], s[28:29]
	v_mov_b64_e32 v[34:35], s[28:29]
	v_mov_b64_e32 v[22:23], s[30:31]
	v_mov_b64_e32 v[18:19], s[30:31]
	v_mov_b64_e32 v[6:7], s[30:31]
	v_mfma_f32_16x16x128_f8f6f4 v[38:41], v[100:107], v[116:123], v[38:41]
	v_mfma_f32_16x16x128_f8f6f4 v[34:37], v[108:115], v[116:123], v[34:37]
	v_mfma_f32_16x16x128_f8f6f4 v[20:23], v[100:107], v[124:131], v[20:23]
	v_mfma_f32_16x16x128_f8f6f4 v[16:19], v[108:115], v[124:131], v[16:19]
	v_mfma_f32_16x16x128_f8f6f4 v[4:7], v[100:107], v[132:139], v[4:7]
	v_mfma_f32_16x16x128_f8f6f4 v[0:3], v[108:115], v[132:139], v[0:3]
	s_setprio 0
	s_barrier
	s_mov_b64 s[8:9], 0x100
	s_mov_b32 m0, s85
	v_lshl_add_u64 v[100:101], v[78:79], 0, s[8:9]
	global_load_lds_dwordx4 v[100:101], off
	v_lshl_add_u64 v[100:101], v[80:81], 0, s[8:9]
	s_mov_b32 m0, s84
	s_nop 0
	global_load_lds_dwordx4 v[100:101], off
	v_lshl_add_u64 v[100:101], s[34:35], 0, v[32:33]
	s_mov_b32 m0, s87
	s_nop 0
	global_load_lds_dwordx4 v[100:101], off
	v_lshl_add_u64 v[100:101], s[34:35], 0, v[166:167]
	s_mov_b32 m0, s86
	s_nop 0
	global_load_lds_dwordx4 v[100:101], off
	v_lshl_add_u64 v[100:101], v[90:91], 0, s[8:9]
	s_mov_b32 m0, s77
	s_nop 0
	global_load_lds_dwordx4 v[100:101], off
	v_lshl_add_u64 v[100:101], v[92:93], 0, s[8:9]
	s_mov_b32 m0, s83
	s_nop 0
	global_load_lds_dwordx4 v[100:101], off
	s_waitcnt vmcnt(8)
	s_waitcnt lgkmcnt(0)
	s_barrier
	s_barrier
	ds_read_b128 v[100:103], v96
	ds_read_b128 v[104:107], v96 offset:1024
	ds_read_b128 v[108:111], v96 offset:2048
	ds_read_b128 v[112:115], v96 offset:3072
	ds_read_b128 v[116:119], v95
	ds_read_b128 v[120:123], v95 offset:1024
	ds_read_b128 v[124:127], v95 offset:2048
	ds_read_b128 v[128:131], v95 offset:3072
	v_readlane_b32 s8, v254, 20
	v_readlane_b32 s9, v254, 21
	s_mov_b32 m0, s66
	ds_read_b128 v[132:135], v94 offset:32768
	ds_read_b128 v[136:139], v94 offset:33792
	ds_read_b128 v[140:143], v94 offset:34816
	ds_read_b128 v[144:147], v94 offset:35840
	ds_read_b128 v[148:151], v94 offset:36864
	ds_read_b128 v[152:155], v94 offset:37888
	ds_read_b128 v[168:171], v94 offset:38912
	ds_read_b128 v[172:175], v94 offset:39936
	v_lshl_add_u64 v[156:157], s[8:9], 0, v[162:163]
	global_load_lds_dwordx4 v[156:157], off
	v_lshl_add_u64 v[156:157], s[8:9], 0, v[164:165]
	s_mov_b32 m0, s72
	s_nop 0
	global_load_lds_dwordx4 v[156:157], off
	s_waitcnt vmcnt(8)
	s_waitcnt lgkmcnt(0)
	s_barrier
	s_setprio 1
	s_waitcnt lgkmcnt(0)
	v_mfma_f32_16x16x128_f8f6f4 v[62:65], v[100:107], v[132:139], v[62:65]
	v_mfma_f32_16x16x128_f8f6f4 v[58:61], v[108:115], v[132:139], v[58:61]
	v_mfma_f32_16x16x128_f8f6f4 v[46:49], v[100:107], v[140:147], v[46:49]
	v_mfma_f32_16x16x128_f8f6f4 v[42:45], v[108:115], v[140:147], v[42:45]
	v_mfma_f32_16x16x128_f8f6f4 v[28:31], v[100:107], v[148:155], v[28:31]
	v_mfma_f32_16x16x128_f8f6f4 v[24:27], v[108:115], v[148:155], v[24:27]
	v_mfma_f32_16x16x128_f8f6f4 v[12:15], v[100:107], v[168:175], v[12:15]
	v_mfma_f32_16x16x128_f8f6f4 v[8:11], v[108:115], v[168:175], v[8:11]
	s_setprio 0
	s_setprio 1
	v_mfma_f32_16x16x128_f8f6f4 v[54:57], v[116:123], v[132:139], v[54:57]
	v_mfma_f32_16x16x128_f8f6f4 v[50:53], v[124:131], v[132:139], v[50:53]
	v_mfma_f32_16x16x128_f8f6f4 v[38:41], v[116:123], v[140:147], v[38:41]
	v_mfma_f32_16x16x128_f8f6f4 v[34:37], v[124:131], v[140:147], v[34:37]
	v_mfma_f32_16x16x128_f8f6f4 v[20:23], v[116:123], v[148:155], v[20:23]
	v_mfma_f32_16x16x128_f8f6f4 v[16:19], v[124:131], v[148:155], v[16:19]
	v_mfma_f32_16x16x128_f8f6f4 v[4:7], v[116:123], v[168:175], v[4:7]
	v_mfma_f32_16x16x128_f8f6f4 v[0:3], v[124:131], v[168:175], v[0:3]
	s_setprio 0
	s_barrier
	s_mov_b64 s[8:9], 0x180
	s_mov_b32 m0, s2
	v_lshl_add_u64 v[100:101], v[78:79], 0, s[8:9]
	global_load_lds_dwordx4 v[100:101], off
	v_lshl_add_u64 v[100:101], v[80:81], 0, s[8:9]
	s_mov_b32 m0, s73
	s_nop 0
	global_load_lds_dwordx4 v[100:101], off
	v_lshl_add_u64 v[100:101], s[20:21], 0, v[32:33]
	s_mov_b32 m0, s75
	s_nop 0
	global_load_lds_dwordx4 v[100:101], off
	v_lshl_add_u64 v[100:101], s[20:21], 0, v[166:167]
	s_mov_b32 m0, s76
	s_nop 0
	global_load_lds_dwordx4 v[100:101], off
	v_lshl_add_u64 v[100:101], v[90:91], 0, s[8:9]
	s_mov_b32 m0, s67
	s_nop 0
	global_load_lds_dwordx4 v[100:101], off
	v_lshl_add_u64 v[100:101], v[92:93], 0, s[8:9]
	s_mov_b32 m0, s74
	s_nop 0
	global_load_lds_dwordx4 v[100:101], off
	s_waitcnt vmcnt(8)
	s_waitcnt lgkmcnt(0)
	s_barrier
	s_barrier
	ds_read_b128 v[100:103], v98
	ds_read_b128 v[104:107], v98 offset:1024
	ds_read_b128 v[108:111], v98 offset:2048
	ds_read_b128 v[112:115], v98 offset:3072
	ds_read_b128 v[116:119], v97
	ds_read_b128 v[120:123], v97 offset:1024
	ds_read_b128 v[124:127], v97 offset:2048
	ds_read_b128 v[128:131], v97 offset:3072
	v_readlane_b32 s8, v254, 22
	v_readlane_b32 s9, v254, 23
	s_mov_b32 m0, s89
	ds_read_b128 v[132:135], v94
	ds_read_b128 v[136:139], v94 offset:1024
	ds_read_b128 v[140:143], v94 offset:2048
	ds_read_b128 v[144:147], v94 offset:3072
	ds_read_b128 v[148:151], v94 offset:4096
	ds_read_b128 v[152:155], v94 offset:5120
	ds_read_b128 v[168:171], v94 offset:6144
	ds_read_b128 v[172:175], v94 offset:7168
	v_lshl_add_u64 v[156:157], s[8:9], 0, v[162:163]
	global_load_lds_dwordx4 v[156:157], off
	v_lshl_add_u64 v[156:157], s[8:9], 0, v[164:165]
	s_mov_b32 m0, s88
	s_nop 0
	global_load_lds_dwordx4 v[156:157], off
	s_waitcnt vmcnt(8)
	s_waitcnt lgkmcnt(0)
	s_barrier
	s_setprio 1
	s_waitcnt lgkmcnt(0)
	v_mfma_f32_16x16x128_f8f6f4 v[62:65], v[100:107], v[132:139], v[62:65]
	v_mfma_f32_16x16x128_f8f6f4 v[58:61], v[108:115], v[132:139], v[58:61]
	v_mfma_f32_16x16x128_f8f6f4 v[46:49], v[100:107], v[140:147], v[46:49]
	v_mfma_f32_16x16x128_f8f6f4 v[42:45], v[108:115], v[140:147], v[42:45]
	v_mfma_f32_16x16x128_f8f6f4 v[28:31], v[100:107], v[148:155], v[28:31]
	v_mfma_f32_16x16x128_f8f6f4 v[24:27], v[108:115], v[148:155], v[24:27]
	v_mfma_f32_16x16x128_f8f6f4 v[12:15], v[100:107], v[168:175], v[12:15]
	v_mfma_f32_16x16x128_f8f6f4 v[8:11], v[108:115], v[168:175], v[8:11]
	s_setprio 0
	s_setprio 1
	v_mfma_f32_16x16x128_f8f6f4 v[54:57], v[116:123], v[132:139], v[54:57]
	v_mfma_f32_16x16x128_f8f6f4 v[50:53], v[124:131], v[132:139], v[50:53]
	v_mfma_f32_16x16x128_f8f6f4 v[38:41], v[116:123], v[140:147], v[38:41]
	v_mfma_f32_16x16x128_f8f6f4 v[34:37], v[124:131], v[140:147], v[34:37]
	v_mfma_f32_16x16x128_f8f6f4 v[20:23], v[116:123], v[148:155], v[20:23]
	v_mfma_f32_16x16x128_f8f6f4 v[16:19], v[124:131], v[148:155], v[16:19]
	v_mfma_f32_16x16x128_f8f6f4 v[4:7], v[116:123], v[168:175], v[4:7]
	v_mfma_f32_16x16x128_f8f6f4 v[0:3], v[124:131], v[168:175], v[0:3]
	s_setprio 0
	s_barrier
	s_mov_b64 s[8:9], 0x200
	s_mov_b32 m0, s85
	v_lshl_add_u64 v[100:101], v[78:79], 0, s[8:9]
	global_load_lds_dwordx4 v[100:101], off
	v_lshl_add_u64 v[100:101], v[80:81], 0, s[8:9]
	s_mov_b32 m0, s84
	s_nop 0
	global_load_lds_dwordx4 v[100:101], off
	v_lshl_add_u64 v[100:101], s[18:19], 0, v[32:33]
	s_mov_b32 m0, s87
	s_nop 0
	global_load_lds_dwordx4 v[100:101], off
	v_lshl_add_u64 v[100:101], s[18:19], 0, v[166:167]
	s_mov_b32 m0, s86
	s_nop 0
	global_load_lds_dwordx4 v[100:101], off
	v_lshl_add_u64 v[100:101], v[90:91], 0, s[8:9]
	s_mov_b32 m0, s77
	s_nop 0
	global_load_lds_dwordx4 v[100:101], off
	v_lshl_add_u64 v[100:101], v[92:93], 0, s[8:9]
	s_mov_b32 m0, s83
	s_nop 0
	global_load_lds_dwordx4 v[100:101], off
	s_waitcnt vmcnt(8)
	s_waitcnt lgkmcnt(0)
	s_barrier
	s_barrier
	ds_read_b128 v[100:103], v96
	ds_read_b128 v[104:107], v96 offset:1024
	ds_read_b128 v[108:111], v96 offset:2048
	ds_read_b128 v[112:115], v96 offset:3072
	ds_read_b128 v[116:119], v95
	ds_read_b128 v[120:123], v95 offset:1024
	ds_read_b128 v[124:127], v95 offset:2048
	ds_read_b128 v[128:131], v95 offset:3072
	v_readlane_b32 s8, v254, 24
	v_readlane_b32 s9, v254, 25
	s_mov_b32 m0, s66
	ds_read_b128 v[132:135], v94 offset:32768
	ds_read_b128 v[136:139], v94 offset:33792
	ds_read_b128 v[140:143], v94 offset:34816
	ds_read_b128 v[144:147], v94 offset:35840
	ds_read_b128 v[148:151], v94 offset:36864
	ds_read_b128 v[152:155], v94 offset:37888
	ds_read_b128 v[168:171], v94 offset:38912
	ds_read_b128 v[172:175], v94 offset:39936
	v_lshl_add_u64 v[156:157], s[8:9], 0, v[162:163]
	global_load_lds_dwordx4 v[156:157], off
	v_lshl_add_u64 v[156:157], s[8:9], 0, v[164:165]
	s_mov_b32 m0, s72
	s_nop 0
	global_load_lds_dwordx4 v[156:157], off
	s_waitcnt vmcnt(8)
	s_waitcnt lgkmcnt(0)
	s_barrier
	s_setprio 1
	s_waitcnt lgkmcnt(0)
	v_mfma_f32_16x16x128_f8f6f4 v[62:65], v[100:107], v[132:139], v[62:65]
	v_mfma_f32_16x16x128_f8f6f4 v[58:61], v[108:115], v[132:139], v[58:61]
	v_mfma_f32_16x16x128_f8f6f4 v[46:49], v[100:107], v[140:147], v[46:49]
	v_mfma_f32_16x16x128_f8f6f4 v[42:45], v[108:115], v[140:147], v[42:45]
	v_mfma_f32_16x16x128_f8f6f4 v[28:31], v[100:107], v[148:155], v[28:31]
	v_mfma_f32_16x16x128_f8f6f4 v[24:27], v[108:115], v[148:155], v[24:27]
	v_mfma_f32_16x16x128_f8f6f4 v[12:15], v[100:107], v[168:175], v[12:15]
	v_mfma_f32_16x16x128_f8f6f4 v[8:11], v[108:115], v[168:175], v[8:11]
	s_setprio 0
	s_setprio 1
	v_mfma_f32_16x16x128_f8f6f4 v[54:57], v[116:123], v[132:139], v[54:57]
	v_mfma_f32_16x16x128_f8f6f4 v[50:53], v[124:131], v[132:139], v[50:53]
	v_mfma_f32_16x16x128_f8f6f4 v[38:41], v[116:123], v[140:147], v[38:41]
	v_mfma_f32_16x16x128_f8f6f4 v[34:37], v[124:131], v[140:147], v[34:37]
	v_mfma_f32_16x16x128_f8f6f4 v[20:23], v[116:123], v[148:155], v[20:23]
	v_mfma_f32_16x16x128_f8f6f4 v[16:19], v[124:131], v[148:155], v[16:19]
	v_mfma_f32_16x16x128_f8f6f4 v[4:7], v[116:123], v[168:175], v[4:7]
	v_mfma_f32_16x16x128_f8f6f4 v[0:3], v[124:131], v[168:175], v[0:3]
	s_setprio 0
	s_barrier
	s_mov_b64 s[8:9], 0x280
	s_mov_b32 m0, s2
	v_lshl_add_u64 v[100:101], v[78:79], 0, s[8:9]
	global_load_lds_dwordx4 v[100:101], off
	v_lshl_add_u64 v[100:101], v[80:81], 0, s[8:9]
	s_mov_b32 m0, s73
	s_nop 0
	global_load_lds_dwordx4 v[100:101], off
	v_lshl_add_u64 v[100:101], s[16:17], 0, v[32:33]
	s_mov_b32 m0, s75
	s_nop 0
	global_load_lds_dwordx4 v[100:101], off
	v_lshl_add_u64 v[100:101], s[16:17], 0, v[166:167]
	s_mov_b32 m0, s76
	s_nop 0
	global_load_lds_dwordx4 v[100:101], off
	v_lshl_add_u64 v[100:101], v[90:91], 0, s[8:9]
	s_mov_b32 m0, s67
	s_nop 0
	global_load_lds_dwordx4 v[100:101], off
	v_lshl_add_u64 v[100:101], v[92:93], 0, s[8:9]
	s_mov_b32 m0, s74
	s_nop 0
	global_load_lds_dwordx4 v[100:101], off
	s_waitcnt vmcnt(8)
	s_waitcnt lgkmcnt(0)
	s_barrier
	s_barrier
	ds_read_b128 v[100:103], v98
	ds_read_b128 v[104:107], v98 offset:1024
	ds_read_b128 v[108:111], v98 offset:2048
	ds_read_b128 v[112:115], v98 offset:3072
	ds_read_b128 v[116:119], v97
	ds_read_b128 v[120:123], v97 offset:1024
	ds_read_b128 v[124:127], v97 offset:2048
	ds_read_b128 v[128:131], v97 offset:3072
	v_readlane_b32 s8, v254, 26
	v_readlane_b32 s9, v254, 27
	s_mov_b32 m0, s89
	ds_read_b128 v[132:135], v94
	ds_read_b128 v[136:139], v94 offset:1024
	ds_read_b128 v[140:143], v94 offset:2048
	ds_read_b128 v[144:147], v94 offset:3072
	ds_read_b128 v[148:151], v94 offset:4096
	ds_read_b128 v[152:155], v94 offset:5120
	ds_read_b128 v[168:171], v94 offset:6144
	ds_read_b128 v[172:175], v94 offset:7168
	v_lshl_add_u64 v[156:157], s[8:9], 0, v[162:163]
	global_load_lds_dwordx4 v[156:157], off
	v_lshl_add_u64 v[156:157], s[8:9], 0, v[164:165]
	s_mov_b32 m0, s88
	s_nop 0
	global_load_lds_dwordx4 v[156:157], off
	s_waitcnt vmcnt(8)
	s_waitcnt lgkmcnt(0)
	s_barrier
	s_setprio 1
	s_waitcnt lgkmcnt(0)
	v_mfma_f32_16x16x128_f8f6f4 v[62:65], v[100:107], v[132:139], v[62:65]
	v_mfma_f32_16x16x128_f8f6f4 v[58:61], v[108:115], v[132:139], v[58:61]
	v_mfma_f32_16x16x128_f8f6f4 v[46:49], v[100:107], v[140:147], v[46:49]
	v_mfma_f32_16x16x128_f8f6f4 v[42:45], v[108:115], v[140:147], v[42:45]
	v_mfma_f32_16x16x128_f8f6f4 v[28:31], v[100:107], v[148:155], v[28:31]
	v_mfma_f32_16x16x128_f8f6f4 v[24:27], v[108:115], v[148:155], v[24:27]
	v_mfma_f32_16x16x128_f8f6f4 v[12:15], v[100:107], v[168:175], v[12:15]
	v_mfma_f32_16x16x128_f8f6f4 v[8:11], v[108:115], v[168:175], v[8:11]
	s_setprio 0
	s_setprio 1
	v_mfma_f32_16x16x128_f8f6f4 v[54:57], v[116:123], v[132:139], v[54:57]
	v_mfma_f32_16x16x128_f8f6f4 v[50:53], v[124:131], v[132:139], v[50:53]
	v_mfma_f32_16x16x128_f8f6f4 v[38:41], v[116:123], v[140:147], v[38:41]
	v_mfma_f32_16x16x128_f8f6f4 v[34:37], v[124:131], v[140:147], v[34:37]
	v_mfma_f32_16x16x128_f8f6f4 v[20:23], v[116:123], v[148:155], v[20:23]
	v_mfma_f32_16x16x128_f8f6f4 v[16:19], v[124:131], v[148:155], v[16:19]
	v_mfma_f32_16x16x128_f8f6f4 v[4:7], v[116:123], v[168:175], v[4:7]
	v_mfma_f32_16x16x128_f8f6f4 v[0:3], v[124:131], v[168:175], v[0:3]
	s_setprio 0
	s_barrier
	s_mov_b64 s[8:9], 0x300
	s_mov_b32 m0, s85
	v_lshl_add_u64 v[100:101], v[78:79], 0, s[8:9]
	global_load_lds_dwordx4 v[100:101], off
	v_lshl_add_u64 v[100:101], v[80:81], 0, s[8:9]
	s_mov_b32 m0, s84
	s_nop 0
	global_load_lds_dwordx4 v[100:101], off
	v_lshl_add_u64 v[100:101], s[14:15], 0, v[32:33]
	s_mov_b32 m0, s87
	s_nop 0
	global_load_lds_dwordx4 v[100:101], off
	v_lshl_add_u64 v[100:101], s[14:15], 0, v[166:167]
	s_mov_b32 m0, s86
	s_nop 0
	global_load_lds_dwordx4 v[100:101], off
	v_lshl_add_u64 v[100:101], v[90:91], 0, s[8:9]
	s_mov_b32 m0, s77
	s_nop 0
	global_load_lds_dwordx4 v[100:101], off
	v_lshl_add_u64 v[100:101], v[92:93], 0, s[8:9]
	s_mov_b32 m0, s83
	s_nop 0
	global_load_lds_dwordx4 v[100:101], off
	s_waitcnt vmcnt(8)
	s_waitcnt lgkmcnt(0)
	s_barrier
	s_barrier
	ds_read_b128 v[100:103], v96
	ds_read_b128 v[104:107], v96 offset:1024
	ds_read_b128 v[108:111], v96 offset:2048
	ds_read_b128 v[112:115], v96 offset:3072
	ds_read_b128 v[116:119], v95
	ds_read_b128 v[120:123], v95 offset:1024
	ds_read_b128 v[124:127], v95 offset:2048
	ds_read_b128 v[128:131], v95 offset:3072
	v_readlane_b32 s8, v254, 28
	v_readlane_b32 s9, v254, 29
	s_mov_b32 m0, s66
	ds_read_b128 v[132:135], v94 offset:32768
	ds_read_b128 v[136:139], v94 offset:33792
	ds_read_b128 v[140:143], v94 offset:34816
	ds_read_b128 v[144:147], v94 offset:35840
	ds_read_b128 v[148:151], v94 offset:36864
	ds_read_b128 v[152:155], v94 offset:37888
	ds_read_b128 v[168:171], v94 offset:38912
	ds_read_b128 v[172:175], v94 offset:39936
	v_lshl_add_u64 v[156:157], s[8:9], 0, v[162:163]
	global_load_lds_dwordx4 v[156:157], off
	v_lshl_add_u64 v[156:157], s[8:9], 0, v[164:165]
	s_mov_b32 m0, s72
	s_nop 0
	global_load_lds_dwordx4 v[156:157], off
	s_waitcnt vmcnt(8)
	s_waitcnt lgkmcnt(0)
	s_barrier
	s_setprio 1
	s_waitcnt lgkmcnt(0)
	v_mfma_f32_16x16x128_f8f6f4 v[62:65], v[100:107], v[132:139], v[62:65]
	v_mfma_f32_16x16x128_f8f6f4 v[58:61], v[108:115], v[132:139], v[58:61]
	v_mfma_f32_16x16x128_f8f6f4 v[46:49], v[100:107], v[140:147], v[46:49]
	v_mfma_f32_16x16x128_f8f6f4 v[42:45], v[108:115], v[140:147], v[42:45]
	v_mfma_f32_16x16x128_f8f6f4 v[28:31], v[100:107], v[148:155], v[28:31]
	v_mfma_f32_16x16x128_f8f6f4 v[24:27], v[108:115], v[148:155], v[24:27]
	v_mfma_f32_16x16x128_f8f6f4 v[12:15], v[100:107], v[168:175], v[12:15]
	v_mfma_f32_16x16x128_f8f6f4 v[8:11], v[108:115], v[168:175], v[8:11]
	s_setprio 0
	s_setprio 1
	v_mfma_f32_16x16x128_f8f6f4 v[54:57], v[116:123], v[132:139], v[54:57]
	v_mfma_f32_16x16x128_f8f6f4 v[50:53], v[124:131], v[132:139], v[50:53]
	v_mfma_f32_16x16x128_f8f6f4 v[38:41], v[116:123], v[140:147], v[38:41]
	v_mfma_f32_16x16x128_f8f6f4 v[34:37], v[124:131], v[140:147], v[34:37]
	v_mfma_f32_16x16x128_f8f6f4 v[20:23], v[116:123], v[148:155], v[20:23]
	v_mfma_f32_16x16x128_f8f6f4 v[16:19], v[124:131], v[148:155], v[16:19]
	v_mfma_f32_16x16x128_f8f6f4 v[4:7], v[116:123], v[168:175], v[4:7]
	v_mfma_f32_16x16x128_f8f6f4 v[0:3], v[124:131], v[168:175], v[0:3]
	s_setprio 0
	s_barrier
	s_mov_b64 s[8:9], 0x380
	s_mov_b32 m0, s2
	v_lshl_add_u64 v[100:101], v[78:79], 0, s[8:9]
	global_load_lds_dwordx4 v[100:101], off
	v_lshl_add_u64 v[100:101], v[80:81], 0, s[8:9]
	s_mov_b32 m0, s73
	s_nop 0
	global_load_lds_dwordx4 v[100:101], off
	v_lshl_add_u64 v[100:101], s[10:11], 0, v[32:33]
	s_mov_b32 m0, s75
	s_nop 0
	global_load_lds_dwordx4 v[100:101], off
	v_lshl_add_u64 v[100:101], s[10:11], 0, v[166:167]
	s_mov_b32 m0, s76
	s_nop 0
	global_load_lds_dwordx4 v[100:101], off
	v_lshl_add_u64 v[100:101], v[90:91], 0, s[8:9]
	s_mov_b32 m0, s67
	s_nop 0
	global_load_lds_dwordx4 v[100:101], off
	v_lshl_add_u64 v[100:101], v[92:93], 0, s[8:9]
	s_mov_b32 m0, s74
	s_nop 0
	global_load_lds_dwordx4 v[100:101], off
	s_waitcnt vmcnt(8)
	s_waitcnt lgkmcnt(0)
	s_barrier
	s_barrier
	ds_read_b128 v[100:103], v98
	ds_read_b128 v[104:107], v98 offset:1024
	ds_read_b128 v[108:111], v98 offset:2048
	ds_read_b128 v[112:115], v98 offset:3072
	ds_read_b128 v[116:119], v97
	ds_read_b128 v[120:123], v97 offset:1024
	ds_read_b128 v[124:127], v97 offset:2048
	ds_read_b128 v[128:131], v97 offset:3072
	v_readlane_b32 s8, v254, 32
	v_readlane_b32 s9, v254, 33
	s_mov_b32 m0, s89
	ds_read_b128 v[132:135], v94
	ds_read_b128 v[136:139], v94 offset:1024
	ds_read_b128 v[140:143], v94 offset:2048
	ds_read_b128 v[144:147], v94 offset:3072
	ds_read_b128 v[148:151], v94 offset:4096
	ds_read_b128 v[152:155], v94 offset:5120
	ds_read_b128 v[166:169], v94 offset:6144
	ds_read_b128 v[170:173], v94 offset:7168
	v_lshl_add_u64 v[98:99], s[8:9], 0, v[162:163]
	global_load_lds_dwordx4 v[98:99], off
	v_lshl_add_u64 v[98:99], s[8:9], 0, v[164:165]
	s_mov_b32 m0, s88
	s_nop 0
	global_load_lds_dwordx4 v[98:99], off
	s_waitcnt vmcnt(8)
	s_waitcnt lgkmcnt(0)
	s_barrier
	s_setprio 1
	s_waitcnt lgkmcnt(0)
	v_mfma_f32_16x16x128_f8f6f4 v[62:65], v[100:107], v[132:139], v[62:65]
	v_mfma_f32_16x16x128_f8f6f4 v[58:61], v[108:115], v[132:139], v[58:61]
	v_mfma_f32_16x16x128_f8f6f4 v[46:49], v[100:107], v[140:147], v[46:49]
	v_mfma_f32_16x16x128_f8f6f4 v[42:45], v[108:115], v[140:147], v[42:45]
	v_mfma_f32_16x16x128_f8f6f4 v[28:31], v[100:107], v[148:155], v[28:31]
	v_mfma_f32_16x16x128_f8f6f4 v[24:27], v[108:115], v[148:155], v[24:27]
	v_mfma_f32_16x16x128_f8f6f4 v[12:15], v[100:107], v[166:173], v[12:15]
	v_mfma_f32_16x16x128_f8f6f4 v[8:11], v[108:115], v[166:173], v[8:11]
	s_setprio 0
	s_setprio 1
	v_mfma_f32_16x16x128_f8f6f4 v[54:57], v[116:123], v[132:139], v[54:57]
	v_mfma_f32_16x16x128_f8f6f4 v[50:53], v[124:131], v[132:139], v[50:53]
	v_mfma_f32_16x16x128_f8f6f4 v[38:41], v[116:123], v[140:147], v[38:41]
	v_mfma_f32_16x16x128_f8f6f4 v[34:37], v[124:131], v[140:147], v[34:37]
	v_mfma_f32_16x16x128_f8f6f4 v[20:23], v[116:123], v[148:155], v[20:23]
	v_mfma_f32_16x16x128_f8f6f4 v[16:19], v[124:131], v[148:155], v[16:19]
	v_mfma_f32_16x16x128_f8f6f4 v[4:7], v[116:123], v[166:173], v[4:7]
	v_mfma_f32_16x16x128_f8f6f4 v[0:3], v[124:131], v[166:173], v[0:3]
	s_setprio 0
	s_barrier
	s_mov_b32 m0, s85
	s_nop 0
	global_load_lds_dwordx4 v[78:79], off
	s_mov_b32 m0, s84
	s_nop 0
	global_load_lds_dwordx4 v[80:81], off
	s_mov_b32 m0, s87
	s_nop 0
	global_load_lds_dwordx4 v[82:83], off
	s_mov_b32 m0, s86
	s_nop 0
	global_load_lds_dwordx4 v[84:85], off
	s_mov_b32 m0, s77
	s_nop 0
	global_load_lds_dwordx4 v[90:91], off
	s_mov_b32 m0, s83
	s_nop 0
	global_load_lds_dwordx4 v[92:93], off
	s_waitcnt vmcnt(8)
	s_waitcnt lgkmcnt(0)
	s_barrier
	s_barrier
	ds_read_b128 v[78:81], v96
	ds_read_b128 v[82:85], v96 offset:1024
	ds_read_b128 v[98:101], v96 offset:2048
	ds_read_b128 v[102:105], v96 offset:3072
	ds_read_b128 v[106:109], v95
	ds_read_b128 v[110:113], v95 offset:1024
	ds_read_b128 v[114:117], v95 offset:2048
	ds_read_b128 v[118:121], v95 offset:3072
	s_mov_b32 m0, s66
	ds_read_b128 v[122:125], v94 offset:32768
	ds_read_b128 v[126:129], v94 offset:33792
	ds_read_b128 v[130:133], v94 offset:34816
	ds_read_b128 v[134:137], v94 offset:35840
	ds_read_b128 v[138:141], v94 offset:36864
	ds_read_b128 v[142:145], v94 offset:37888
	ds_read_b128 v[90:93], v94 offset:38912
	ds_read_b128 v[94:97], v94 offset:39936
	global_load_lds_dwordx4 v[86:87], off
	s_mov_b32 m0, s72
	s_nop 0
	global_load_lds_dwordx4 v[88:89], off
	s_waitcnt vmcnt(8)
	s_waitcnt lgkmcnt(0)
	s_barrier
	s_setprio 1
	s_waitcnt lgkmcnt(0)
	v_mfma_f32_16x16x128_f8f6f4 v[62:65], v[78:85], v[122:129], v[62:65]
	v_mfma_f32_16x16x128_f8f6f4 v[58:61], v[98:105], v[122:129], v[58:61]
	v_mfma_f32_16x16x128_f8f6f4 v[46:49], v[78:85], v[130:137], v[46:49]
	v_mfma_f32_16x16x128_f8f6f4 v[42:45], v[98:105], v[130:137], v[42:45]
	v_mfma_f32_16x16x128_f8f6f4 v[28:31], v[78:85], v[138:145], v[28:31]
	v_mfma_f32_16x16x128_f8f6f4 v[24:27], v[98:105], v[138:145], v[24:27]
	v_mfma_f32_16x16x128_f8f6f4 v[12:15], v[78:85], v[90:97], v[12:15]
	v_mfma_f32_16x16x128_f8f6f4 v[8:11], v[98:105], v[90:97], v[8:11]
	s_setprio 0
	s_setprio 1
	v_mfma_f32_16x16x128_f8f6f4 v[54:57], v[106:113], v[122:129], v[54:57]
	v_mfma_f32_16x16x128_f8f6f4 v[50:53], v[114:121], v[122:129], v[50:53]
	v_mfma_f32_16x16x128_f8f6f4 v[38:41], v[106:113], v[130:137], v[38:41]
	v_mfma_f32_16x16x128_f8f6f4 v[34:37], v[114:121], v[130:137], v[34:37]
	v_mfma_f32_16x16x128_f8f6f4 v[20:23], v[106:113], v[138:145], v[20:23]
	v_mfma_f32_16x16x128_f8f6f4 v[16:19], v[114:121], v[138:145], v[16:19]
	v_mfma_f32_16x16x128_f8f6f4 v[4:7], v[106:113], v[90:97], v[4:7]
	v_mfma_f32_16x16x128_f8f6f4 v[0:3], v[114:121], v[90:97], v[0:3]
	s_setprio 0
	s_barrier
	s_mov_b32 m0, s2
	s_nop 0
	global_load_lds_dwordx4 v[68:69], off
	s_mov_b32 m0, s73
	s_nop 0
	global_load_lds_dwordx4 v[70:71], off
	s_mov_b32 m0, s75
	s_nop 0
	global_load_lds_dwordx4 v[74:75], off
	s_mov_b32 m0, s76
	s_nop 0
	global_load_lds_dwordx4 v[76:77], off
	s_mov_b32 m0, s67
	s_nop 0
	global_load_lds_dwordx4 v[66:67], off
	s_mov_b32 m0, s74
	s_nop 0
	global_load_lds_dwordx4 v[72:73], off
	s_waitcnt vmcnt(8)
	s_waitcnt lgkmcnt(0)
	s_barrier
	s_barrier
	s_cbranch_scc1 .LBB0_487
	s_barrier
